# LRU gate block: 8 elements at a time in op-major order with packed f32 ops
# speedup vs baseline: 1.0198x; 1.0040x over previous
; #define LAS __attribute__((address_space(3)))
; __device__ __forceinline__ float sigmoidf_(float x) { return __builtin_amdgcn_rcpf(1.f + __expf(-x)); }
; __device__ __forceinline__ void lru_chain(unsigned char* ws_, const float* const* in_, int l_, LAS unsigned char* lds, int tid, int bid, int G) {
;     ...
;             { const int tok = 16 * w + j; bf16x8 bfr[2];
; #pragma unroll
;               for (int c = 0; c < 2; ++c) bfr[c] = *(const LAS bf16x8*)(UB + tok * 144 + kq * 16 + c * 64);
; #pragma unroll
;               for (int ot = 0; ot < 4; ++ot) { f32x4 da = (f32x4){0.f, 0.f, 0.f, 0.f}, dx = da;
; #pragma unroll
;                   for (int c = 0; c < 2; ++c) { const bf16x8 fa = *(const LAS bf16x8*)(WT + (16 * ot + j) * 144 + kq * 16 + c * 64), fx = *(const LAS bf16x8*)(WT + (64 + 16 * ot + j) * 144 + kq * 16 + c * 64);
;                       da = __builtin_amdgcn_mfma_f32_16x16x32_bf16(fa, bfr[c], da, 0, 0, 0); dx = __builtin_amdgcn_mfma_f32_16x16x32_bf16(fx, bfr[c], dx, 0, 0, 0); }
;                   const int ch = 16 * ot + 4 * kq;
;                   const f32x4 ba4 = *(const LAS f32x4*)(PRM + ch), bx4 = *(const LAS f32x4*)(PRM + 64 + ch), sp4 = *(const LAS f32x4*)(PRM + 128 + ch);
;                   const f32x4 u4 = *(const LAS f32x4*)(B_ + tok * 68 + ch); f32x4 a4, b4;
; #pragma unroll
;                   for (int e = 0; e < 4; ++e) { const float rg = sigmoidf_(da[e] + ba4[e]), ig = sigmoidf_(dx[e] + bx4[e]); const float la = -8.0f * rg * sp4[e];
;                       const float av_ = __expf(la); a4[e] = av_; b4[e] = sqrtf(fmaxf(1.0f - av_ * av_, 0.f)) * ig * u4[e]; }
;                   *(LAS f32x4*)(A_ + tok * 68 + ch) = a4; *(LAS f32x4*)(B_ + tok * 68 + ch) = b4; } }
.LBB0_201:
	v_add_u32_e32 v1, v160, v161
	ds_read_b128 v[76:79], v1
	ds_read_b128 v[72:75], v1 offset:64
	s_lshl_b32 s2, s85, 6
	s_and_b32 s2, s2, 64
	s_mov_b32 s3, s80
	s_mov_b32 s6, 0xbfb8aa3b
	s_mov_b32 s10, 0x3fb8aa3b
	s_mov_b32 s98, 0xc1000000
	s_mov_b32 s100, 1.0
	v_mov_b32_e32 v2, 0x4f800000
	v_mov_b32_e32 v3, 0x37800000
	ds_read_b128 v[236:239], v203 offset:0
	ds_read_b128 v[244:247], v203 offset:9216
	ds_read_b128 v[180:183], v203 offset:64
	ds_read_b128 v[240:243], v203 offset:9280
	ds_read_b128 v[96:99], v166
	ds_read_b128 v[208:211], v167
	ds_read_b128 v[216:219], v168
	ds_read_b128 v[224:227], v169 offset:53248
	ds_read_b128 v[100:103], v170
	ds_read_b128 v[212:215], v171
	ds_read_b128 v[220:223], v172
	ds_read_b128 v[228:231], v169 offset:53312
	s_waitcnt lgkmcnt(11)
	v_mfma_f32_16x16x32_bf16 v[80:83], v[236:239], v[76:79], 0
	s_waitcnt lgkmcnt(10)
	v_mfma_f32_16x16x32_bf16 v[88:91], v[244:247], v[76:79], 0
	s_waitcnt lgkmcnt(9)
	v_mfma_f32_16x16x32_bf16 v[80:83], v[180:183], v[72:75], v[80:83]
	s_waitcnt lgkmcnt(8)
	v_mfma_f32_16x16x32_bf16 v[88:91], v[240:243], v[72:75], v[88:91]
	ds_read_b128 v[236:239], v203 offset:2304
	ds_read_b128 v[244:247], v203 offset:11520
	ds_read_b128 v[180:183], v203 offset:2368
	ds_read_b128 v[240:243], v203 offset:11584
	s_waitcnt lgkmcnt(3)
	v_mfma_f32_16x16x32_bf16 v[84:87], v[236:239], v[76:79], 0
	s_waitcnt lgkmcnt(2)
	v_mfma_f32_16x16x32_bf16 v[92:95], v[244:247], v[76:79], 0
	s_waitcnt lgkmcnt(1)
	v_mfma_f32_16x16x32_bf16 v[84:87], v[180:183], v[72:75], v[84:87]
	s_waitcnt lgkmcnt(0)
	v_mfma_f32_16x16x32_bf16 v[92:95], v[240:243], v[72:75], v[92:95]
	s_waitcnt lgkmcnt(0)
	s_nop 7
	v_pk_add_f32 v[80:81], v[80:81], v[96:97]
	v_pk_add_f32 v[82:83], v[82:83], v[98:99]
	v_pk_add_f32 v[84:85], v[84:85], v[100:101]
	v_pk_add_f32 v[86:87], v[86:87], v[102:103]
	v_pk_mul_f32 v[80:81], v[80:81], s[6:7] op_sel_hi:[1,0]
	v_pk_mul_f32 v[82:83], v[82:83], s[6:7] op_sel_hi:[1,0]
	v_pk_mul_f32 v[84:85], v[84:85], s[6:7] op_sel_hi:[1,0]
	v_pk_mul_f32 v[86:87], v[86:87], s[6:7] op_sel_hi:[1,0]
	v_exp_f32_e32 v80, v80
	v_exp_f32_e32 v81, v81
	v_exp_f32_e32 v82, v82
	v_exp_f32_e32 v83, v83
	v_exp_f32_e32 v84, v84
	v_exp_f32_e32 v85, v85
	v_exp_f32_e32 v86, v86
	v_exp_f32_e32 v87, v87
	v_pk_add_f32 v[88:89], v[88:89], v[208:209]
	v_pk_add_f32 v[90:91], v[90:91], v[210:211]
	v_pk_add_f32 v[92:93], v[92:93], v[212:213]
	v_pk_add_f32 v[94:95], v[94:95], v[214:215]
	v_pk_add_f32 v[80:81], v[80:81], s[100:101] op_sel_hi:[1,0]
	v_pk_add_f32 v[82:83], v[82:83], s[100:101] op_sel_hi:[1,0]
	v_pk_add_f32 v[84:85], v[84:85], s[100:101] op_sel_hi:[1,0]
	v_pk_add_f32 v[86:87], v[86:87], s[100:101] op_sel_hi:[1,0]
	v_rcp_f32_e32 v80, v80
	v_rcp_f32_e32 v81, v81
	v_rcp_f32_e32 v82, v82
	v_rcp_f32_e32 v83, v83
	v_rcp_f32_e32 v84, v84
	v_rcp_f32_e32 v85, v85
	v_rcp_f32_e32 v86, v86
	v_rcp_f32_e32 v87, v87
	v_pk_mul_f32 v[88:89], v[88:89], s[6:7] op_sel_hi:[1,0]
	v_pk_mul_f32 v[90:91], v[90:91], s[6:7] op_sel_hi:[1,0]
	v_pk_mul_f32 v[92:93], v[92:93], s[6:7] op_sel_hi:[1,0]
	v_pk_mul_f32 v[94:95], v[94:95], s[6:7] op_sel_hi:[1,0]
	v_pk_mul_f32 v[80:81], v[80:81], s[98:99] op_sel_hi:[1,0]
	v_pk_mul_f32 v[82:83], v[82:83], s[98:99] op_sel_hi:[1,0]
	v_pk_mul_f32 v[84:85], v[84:85], s[98:99] op_sel_hi:[1,0]
	v_pk_mul_f32 v[86:87], v[86:87], s[98:99] op_sel_hi:[1,0]
	v_pk_mul_f32 v[80:81], v[216:217], v[80:81]
	v_pk_mul_f32 v[82:83], v[218:219], v[82:83]
	v_pk_mul_f32 v[84:85], v[220:221], v[84:85]
	v_pk_mul_f32 v[86:87], v[222:223], v[86:87]
	v_pk_mul_f32 v[80:81], v[80:81], s[10:11] op_sel_hi:[1,0]
	v_pk_mul_f32 v[82:83], v[82:83], s[10:11] op_sel_hi:[1,0]
	v_pk_mul_f32 v[84:85], v[84:85], s[10:11] op_sel_hi:[1,0]
	v_pk_mul_f32 v[86:87], v[86:87], s[10:11] op_sel_hi:[1,0]
	v_exp_f32_e32 v80, v80
	v_exp_f32_e32 v81, v81
	v_exp_f32_e32 v82, v82
	v_exp_f32_e32 v83, v83
	v_exp_f32_e32 v84, v84
	v_exp_f32_e32 v85, v85
	v_exp_f32_e32 v86, v86
	v_exp_f32_e32 v87, v87
	v_exp_f32_e32 v88, v88
	v_exp_f32_e32 v89, v89
	v_exp_f32_e32 v90, v90
	v_exp_f32_e32 v91, v91
	v_exp_f32_e32 v92, v92
	v_exp_f32_e32 v93, v93
	v_exp_f32_e32 v94, v94
	v_exp_f32_e32 v95, v95
	v_pk_fma_f32 v[96:97], v[80:81], v[80:81], s[100:101] op_sel_hi:[1,1,0] neg_lo:[1,0,0] neg_hi:[1,0,0]
	v_pk_fma_f32 v[98:99], v[82:83], v[82:83], s[100:101] op_sel_hi:[1,1,0] neg_lo:[1,0,0] neg_hi:[1,0,0]
	v_pk_fma_f32 v[100:101], v[84:85], v[84:85], s[100:101] op_sel_hi:[1,1,0] neg_lo:[1,0,0] neg_hi:[1,0,0]
	v_pk_fma_f32 v[102:103], v[86:87], v[86:87], s[100:101] op_sel_hi:[1,1,0] neg_lo:[1,0,0] neg_hi:[1,0,0]
	v_max_f32_e32 v96, 0, v96
	v_max_f32_e32 v97, 0, v97
	v_max_f32_e32 v98, 0, v98
	v_max_f32_e32 v99, 0, v99
	v_max_f32_e32 v100, 0, v100
	v_max_f32_e32 v101, 0, v101
	v_max_f32_e32 v102, 0, v102
	v_max_f32_e32 v103, 0, v103
	v_pk_add_f32 v[88:89], v[88:89], s[100:101] op_sel_hi:[1,0]
	v_pk_add_f32 v[90:91], v[90:91], s[100:101] op_sel_hi:[1,0]
	v_pk_add_f32 v[92:93], v[92:93], s[100:101] op_sel_hi:[1,0]
	v_pk_add_f32 v[94:95], v[94:95], s[100:101] op_sel_hi:[1,0]
	v_cmp_gt_f32_e64 s[16:17], s89, v96
	v_cmp_gt_f32_e64 s[18:19], s89, v97
	v_cmp_gt_f32_e64 s[20:21], s89, v98
	v_cmp_gt_f32_e64 s[22:23], s89, v99
	v_cndmask_b32_e64 v216, 1.0, v2, s[16:17]
	v_cndmask_b32_e64 v208, 1.0, v3, s[16:17]
	v_cndmask_b32_e64 v217, 1.0, v2, s[18:19]
	v_cndmask_b32_e64 v209, 1.0, v3, s[18:19]
	v_cndmask_b32_e64 v218, 1.0, v2, s[20:21]
	v_cndmask_b32_e64 v210, 1.0, v3, s[20:21]
	v_cndmask_b32_e64 v219, 1.0, v2, s[22:23]
	v_cndmask_b32_e64 v211, 1.0, v3, s[22:23]
	v_cmp_gt_f32_e64 s[16:17], s89, v100
	v_cmp_gt_f32_e64 s[18:19], s89, v101
	v_cmp_gt_f32_e64 s[20:21], s89, v102
; #define LAS __attribute__((address_space(3)))
; __device__ __forceinline__ float sigmoidf_(float x) { return __builtin_amdgcn_rcpf(1.f + __expf(-x)); }
; __device__ __forceinline__ void lru_chain(unsigned char* ws_, const float* const* in_, int l_, LAS unsigned char* lds, int tid, int bid, int G) {
;     ...
;                       da = __builtin_amdgcn_mfma_f32_16x16x32_bf16(fa, bfr[c], da, 0, 0, 0); dx = __builtin_amdgcn_mfma_f32_16x16x32_bf16(fx, bfr[c], dx, 0, 0, 0); }
;                   const int ch = 16 * ot + 4 * kq;
;                   const f32x4 ba4 = *(const LAS f32x4*)(PRM + ch), bx4 = *(const LAS f32x4*)(PRM + 64 + ch), sp4 = *(const LAS f32x4*)(PRM + 128 + ch);
;                   const f32x4 u4 = *(const LAS f32x4*)(B_ + tok * 68 + ch); f32x4 a4, b4;
; #pragma unroll
;                   for (int e = 0; e < 4; ++e) { const float rg = sigmoidf_(da[e] + ba4[e]), ig = sigmoidf_(dx[e] + bx4[e]); const float la = -8.0f * rg * sp4[e];
;                       const float av_ = __expf(la); a4[e] = av_; b4[e] = sqrtf(fmaxf(1.0f - av_ * av_, 0.f)) * ig * u4[e]; }
;                   *(LAS f32x4*)(A_ + tok * 68 + ch) = a4; *(LAS f32x4*)(B_ + tok * 68 + ch) = b4; } }
	v_cmp_gt_f32_e64 s[22:23], s89, v103
	v_cndmask_b32_e64 v220, 1.0, v2, s[16:17]
	v_cndmask_b32_e64 v212, 1.0, v3, s[16:17]
	v_cndmask_b32_e64 v221, 1.0, v2, s[18:19]
	v_cndmask_b32_e64 v213, 1.0, v3, s[18:19]
	v_cndmask_b32_e64 v222, 1.0, v2, s[20:21]
	v_cndmask_b32_e64 v214, 1.0, v3, s[20:21]
	v_cndmask_b32_e64 v223, 1.0, v2, s[22:23]
	v_cndmask_b32_e64 v215, 1.0, v3, s[22:23]
	v_pk_mul_f32 v[96:97], v[96:97], v[216:217]
	v_pk_mul_f32 v[98:99], v[98:99], v[218:219]
	v_pk_mul_f32 v[100:101], v[100:101], v[220:221]
	v_pk_mul_f32 v[102:103], v[102:103], v[222:223]
	v_sqrt_f32_e32 v216, v96
	v_sqrt_f32_e32 v217, v97
	v_sqrt_f32_e32 v218, v98
	v_sqrt_f32_e32 v219, v99
	v_sqrt_f32_e32 v220, v100
	v_sqrt_f32_e32 v221, v101
	v_sqrt_f32_e32 v222, v102
	v_sqrt_f32_e32 v223, v103
	v_rcp_f32_e32 v88, v88
	v_rcp_f32_e32 v89, v89
	v_rcp_f32_e32 v90, v90
	v_rcp_f32_e32 v91, v91
	v_rcp_f32_e32 v92, v92
	v_rcp_f32_e32 v93, v93
	v_rcp_f32_e32 v94, v94
	v_rcp_f32_e32 v95, v95
	v_add_u32_e32 v236, -1, v216
	v_add_u32_e32 v237, -1, v217
	v_add_u32_e32 v238, -1, v218
	v_add_u32_e32 v239, -1, v219
	v_add_u32_e32 v240, -1, v220
	v_add_u32_e32 v241, -1, v221
	v_add_u32_e32 v242, -1, v222
	v_add_u32_e32 v243, -1, v223
	v_pk_fma_f32 v[244:245], v[236:237], v[216:217], v[96:97] neg_lo:[1,0,0] neg_hi:[1,0,0]
	v_pk_fma_f32 v[246:247], v[238:239], v[218:219], v[98:99] neg_lo:[1,0,0] neg_hi:[1,0,0]
	v_pk_fma_f32 v[248:249], v[240:241], v[220:221], v[100:101] neg_lo:[1,0,0] neg_hi:[1,0,0]
	v_pk_fma_f32 v[250:251], v[242:243], v[222:223], v[102:103] neg_lo:[1,0,0] neg_hi:[1,0,0]
	v_add_u32_e32 v180, 1, v216
	v_add_u32_e32 v181, 1, v217
	v_add_u32_e32 v182, 1, v218
	v_add_u32_e32 v183, 1, v219
	v_add_u32_e32 v232, 1, v220
	v_add_u32_e32 v233, 1, v221
	v_add_u32_e32 v234, 1, v222
	v_add_u32_e32 v235, 1, v223
	v_cmp_ge_f32_e64 s[16:17], 0, v244
	v_cmp_ge_f32_e64 s[18:19], 0, v245
	v_cmp_ge_f32_e64 s[20:21], 0, v246
	v_cmp_ge_f32_e64 s[22:23], 0, v247
	v_cndmask_b32_e64 v236, v216, v236, s[16:17]
	v_cndmask_b32_e64 v237, v217, v237, s[18:19]
	v_cndmask_b32_e64 v238, v218, v238, s[20:21]
	v_cndmask_b32_e64 v239, v219, v239, s[22:23]
	v_cmp_ge_f32_e64 s[16:17], 0, v248
	v_cmp_ge_f32_e64 s[18:19], 0, v249
	v_cmp_ge_f32_e64 s[20:21], 0, v250
	v_cmp_ge_f32_e64 s[22:23], 0, v251
	v_cndmask_b32_e64 v240, v220, v240, s[16:17]
	v_cndmask_b32_e64 v241, v221, v241, s[18:19]
	v_cndmask_b32_e64 v242, v222, v242, s[20:21]
	v_cndmask_b32_e64 v243, v223, v243, s[22:23]
	v_pk_fma_f32 v[244:245], v[180:181], v[216:217], v[96:97] neg_lo:[1,0,0] neg_hi:[1,0,0]
	v_pk_fma_f32 v[246:247], v[182:183], v[218:219], v[98:99] neg_lo:[1,0,0] neg_hi:[1,0,0]
	v_pk_fma_f32 v[248:249], v[232:233], v[220:221], v[100:101] neg_lo:[1,0,0] neg_hi:[1,0,0]
	v_pk_fma_f32 v[250:251], v[234:235], v[222:223], v[102:103] neg_lo:[1,0,0] neg_hi:[1,0,0]
	v_cmp_lt_f32_e64 s[16:17], 0, v244
	v_cmp_lt_f32_e64 s[18:19], 0, v245
	v_cmp_lt_f32_e64 s[20:21], 0, v246
	v_cmp_lt_f32_e64 s[22:23], 0, v247
	v_cndmask_b32_e64 v236, v236, v180, s[16:17]
	v_cndmask_b32_e64 v237, v237, v181, s[18:19]
	v_cndmask_b32_e64 v238, v238, v182, s[20:21]
	v_cndmask_b32_e64 v239, v239, v183, s[22:23]
	v_cmp_lt_f32_e64 s[16:17], 0, v248
	v_cmp_lt_f32_e64 s[18:19], 0, v249
	v_cmp_lt_f32_e64 s[20:21], 0, v250
	v_cmp_lt_f32_e64 s[22:23], 0, v251
	v_cndmask_b32_e64 v240, v240, v232, s[16:17]
	v_cndmask_b32_e64 v241, v241, v233, s[18:19]
	v_cndmask_b32_e64 v242, v242, v234, s[20:21]
	v_cndmask_b32_e64 v243, v243, v235, s[22:23]
	v_pk_mul_f32 v[236:237], v[236:237], v[208:209]
	v_pk_mul_f32 v[238:239], v[238:239], v[210:211]
	v_pk_mul_f32 v[240:241], v[240:241], v[212:213]
	v_pk_mul_f32 v[242:243], v[242:243], v[214:215]
	v_cmp_class_f32_e64 s[16:17], v96, v175
	v_cmp_class_f32_e64 s[18:19], v97, v175
	v_cmp_class_f32_e64 s[20:21], v98, v175
	v_cmp_class_f32_e64 s[22:23], v99, v175
	v_cndmask_b32_e64 v236, v236, v96, s[16:17]
	v_cndmask_b32_e64 v237, v237, v97, s[18:19]
	v_cndmask_b32_e64 v238, v238, v98, s[20:21]
	v_cndmask_b32_e64 v239, v239, v99, s[22:23]
	v_cmp_class_f32_e64 s[16:17], v100, v175
	v_cmp_class_f32_e64 s[18:19], v101, v175
	v_cmp_class_f32_e64 s[20:21], v102, v175
	v_cmp_class_f32_e64 s[22:23], v103, v175
	v_cndmask_b32_e64 v240, v240, v100, s[16:17]
	v_cndmask_b32_e64 v241, v241, v101, s[18:19]
	v_cndmask_b32_e64 v242, v242, v102, s[20:21]
	v_cndmask_b32_e64 v243, v243, v103, s[22:23]
	v_pk_mul_f32 v[88:89], v[88:89], v[236:237]
	v_pk_mul_f32 v[90:91], v[90:91], v[238:239]
	v_pk_mul_f32 v[92:93], v[92:93], v[240:241]
	v_pk_mul_f32 v[94:95], v[94:95], v[242:243]
	v_pk_mul_f32 v[88:89], v[224:225], v[88:89]
	v_pk_mul_f32 v[90:91], v[226:227], v[90:91]
	v_pk_mul_f32 v[92:93], v[228:229], v[92:93]
	v_pk_mul_f32 v[94:95], v[230:231], v[94:95]
	ds_write_b128 v169, v[80:83] offset:18432
	ds_write_b128 v169, v[88:91] offset:53248
	ds_write_b128 v169, v[84:87] offset:18496
	ds_write_b128 v169, v[92:95] offset:53312
	ds_read_b128 v[236:239], v203 offset:4608
	ds_read_b128 v[244:247], v203 offset:13824
	ds_read_b128 v[180:183], v203 offset:4672
	ds_read_b128 v[240:243], v203 offset:13888
	ds_read_b128 v[96:99], v173
	ds_read_b128 v[208:211], v192
	ds_read_b128 v[216:219], v193
	ds_read_b128 v[224:227], v169 offset:53376
	ds_read_b128 v[100:103], v194
	ds_read_b128 v[212:215], v195
	ds_read_b128 v[220:223], v196
	ds_read_b128 v[228:231], v169 offset:53440
	s_waitcnt lgkmcnt(11)
	v_mfma_f32_16x16x32_bf16 v[80:83], v[236:239], v[76:79], 0
	s_waitcnt lgkmcnt(10)
	v_mfma_f32_16x16x32_bf16 v[88:91], v[244:247], v[76:79], 0
	s_waitcnt lgkmcnt(9)
	v_mfma_f32_16x16x32_bf16 v[80:83], v[180:183], v[72:75], v[80:83]
	s_waitcnt lgkmcnt(8)
; #define LAS __attribute__((address_space(3)))
; __device__ __forceinline__ float sigmoidf_(float x) { return __builtin_amdgcn_rcpf(1.f + __expf(-x)); }
; __device__ __forceinline__ void lru_chain(unsigned char* ws_, const float* const* in_, int l_, LAS unsigned char* lds, int tid, int bid, int G) {
;     ...
;                       da = __builtin_amdgcn_mfma_f32_16x16x32_bf16(fa, bfr[c], da, 0, 0, 0); dx = __builtin_amdgcn_mfma_f32_16x16x32_bf16(fx, bfr[c], dx, 0, 0, 0); }
;                   const int ch = 16 * ot + 4 * kq;
;                   const f32x4 ba4 = *(const LAS f32x4*)(PRM + ch), bx4 = *(const LAS f32x4*)(PRM + 64 + ch), sp4 = *(const LAS f32x4*)(PRM + 128 + ch);
;                   const f32x4 u4 = *(const LAS f32x4*)(B_ + tok * 68 + ch); f32x4 a4, b4;
; #pragma unroll
;                   for (int e = 0; e < 4; ++e) { const float rg = sigmoidf_(da[e] + ba4[e]), ig = sigmoidf_(dx[e] + bx4[e]); const float la = -8.0f * rg * sp4[e];
;                       const float av_ = __expf(la); a4[e] = av_; b4[e] = sqrtf(fmaxf(1.0f - av_ * av_, 0.f)) * ig * u4[e]; }
;                   *(LAS f32x4*)(A_ + tok * 68 + ch) = a4; *(LAS f32x4*)(B_ + tok * 68 + ch) = b4; } }
	v_mfma_f32_16x16x32_bf16 v[88:91], v[240:243], v[72:75], v[88:91]
	ds_read_b128 v[236:239], v203 offset:6912
	ds_read_b128 v[244:247], v203 offset:16128
	ds_read_b128 v[180:183], v203 offset:6976
	ds_read_b128 v[240:243], v203 offset:16192
	s_waitcnt lgkmcnt(3)
	v_mfma_f32_16x16x32_bf16 v[84:87], v[236:239], v[76:79], 0
	s_waitcnt lgkmcnt(2)
	v_mfma_f32_16x16x32_bf16 v[92:95], v[244:247], v[76:79], 0
	s_waitcnt lgkmcnt(1)
	v_mfma_f32_16x16x32_bf16 v[84:87], v[180:183], v[72:75], v[84:87]
	s_waitcnt lgkmcnt(0)
	v_mfma_f32_16x16x32_bf16 v[92:95], v[240:243], v[72:75], v[92:95]
	s_waitcnt lgkmcnt(0)
	s_nop 7
	v_pk_add_f32 v[80:81], v[80:81], v[96:97]
	v_pk_add_f32 v[82:83], v[82:83], v[98:99]
	v_pk_add_f32 v[84:85], v[84:85], v[100:101]
	v_pk_add_f32 v[86:87], v[86:87], v[102:103]
	v_pk_mul_f32 v[80:81], v[80:81], s[6:7] op_sel_hi:[1,0]
	v_pk_mul_f32 v[82:83], v[82:83], s[6:7] op_sel_hi:[1,0]
	v_pk_mul_f32 v[84:85], v[84:85], s[6:7] op_sel_hi:[1,0]
	v_pk_mul_f32 v[86:87], v[86:87], s[6:7] op_sel_hi:[1,0]
	v_exp_f32_e32 v80, v80
	v_exp_f32_e32 v81, v81
	v_exp_f32_e32 v82, v82
	v_exp_f32_e32 v83, v83
	v_exp_f32_e32 v84, v84
	v_exp_f32_e32 v85, v85
	v_exp_f32_e32 v86, v86
	v_exp_f32_e32 v87, v87
	v_pk_add_f32 v[88:89], v[88:89], v[208:209]
	v_pk_add_f32 v[90:91], v[90:91], v[210:211]
	v_pk_add_f32 v[92:93], v[92:93], v[212:213]
	v_pk_add_f32 v[94:95], v[94:95], v[214:215]
	v_pk_add_f32 v[80:81], v[80:81], s[100:101] op_sel_hi:[1,0]
	v_pk_add_f32 v[82:83], v[82:83], s[100:101] op_sel_hi:[1,0]
	v_pk_add_f32 v[84:85], v[84:85], s[100:101] op_sel_hi:[1,0]
	v_pk_add_f32 v[86:87], v[86:87], s[100:101] op_sel_hi:[1,0]
	v_rcp_f32_e32 v80, v80
	v_rcp_f32_e32 v81, v81
	v_rcp_f32_e32 v82, v82
	v_rcp_f32_e32 v83, v83
	v_rcp_f32_e32 v84, v84
	v_rcp_f32_e32 v85, v85
	v_rcp_f32_e32 v86, v86
	v_rcp_f32_e32 v87, v87
	v_pk_mul_f32 v[88:89], v[88:89], s[6:7] op_sel_hi:[1,0]
	v_pk_mul_f32 v[90:91], v[90:91], s[6:7] op_sel_hi:[1,0]
	v_pk_mul_f32 v[92:93], v[92:93], s[6:7] op_sel_hi:[1,0]
	v_pk_mul_f32 v[94:95], v[94:95], s[6:7] op_sel_hi:[1,0]
	v_pk_mul_f32 v[80:81], v[80:81], s[98:99] op_sel_hi:[1,0]
	v_pk_mul_f32 v[82:83], v[82:83], s[98:99] op_sel_hi:[1,0]
	v_pk_mul_f32 v[84:85], v[84:85], s[98:99] op_sel_hi:[1,0]
	v_pk_mul_f32 v[86:87], v[86:87], s[98:99] op_sel_hi:[1,0]
	v_pk_mul_f32 v[80:81], v[216:217], v[80:81]
	v_pk_mul_f32 v[82:83], v[218:219], v[82:83]
	v_pk_mul_f32 v[84:85], v[220:221], v[84:85]
	v_pk_mul_f32 v[86:87], v[222:223], v[86:87]
	v_pk_mul_f32 v[80:81], v[80:81], s[10:11] op_sel_hi:[1,0]
	v_pk_mul_f32 v[82:83], v[82:83], s[10:11] op_sel_hi:[1,0]
	v_pk_mul_f32 v[84:85], v[84:85], s[10:11] op_sel_hi:[1,0]
	v_pk_mul_f32 v[86:87], v[86:87], s[10:11] op_sel_hi:[1,0]
	v_exp_f32_e32 v80, v80
	v_exp_f32_e32 v81, v81
	v_exp_f32_e32 v82, v82
	v_exp_f32_e32 v83, v83
	v_exp_f32_e32 v84, v84
	v_exp_f32_e32 v85, v85
	v_exp_f32_e32 v86, v86
	v_exp_f32_e32 v87, v87
	v_exp_f32_e32 v88, v88
	v_exp_f32_e32 v89, v89
	v_exp_f32_e32 v90, v90
	v_exp_f32_e32 v91, v91
	v_exp_f32_e32 v92, v92
	v_exp_f32_e32 v93, v93
	v_exp_f32_e32 v94, v94
	v_exp_f32_e32 v95, v95
	v_pk_fma_f32 v[96:97], v[80:81], v[80:81], s[100:101] op_sel_hi:[1,1,0] neg_lo:[1,0,0] neg_hi:[1,0,0]
	v_pk_fma_f32 v[98:99], v[82:83], v[82:83], s[100:101] op_sel_hi:[1,1,0] neg_lo:[1,0,0] neg_hi:[1,0,0]
	v_pk_fma_f32 v[100:101], v[84:85], v[84:85], s[100:101] op_sel_hi:[1,1,0] neg_lo:[1,0,0] neg_hi:[1,0,0]
	v_pk_fma_f32 v[102:103], v[86:87], v[86:87], s[100:101] op_sel_hi:[1,1,0] neg_lo:[1,0,0] neg_hi:[1,0,0]
	v_max_f32_e32 v96, 0, v96
	v_max_f32_e32 v97, 0, v97
	v_max_f32_e32 v98, 0, v98
	v_max_f32_e32 v99, 0, v99
	v_max_f32_e32 v100, 0, v100
	v_max_f32_e32 v101, 0, v101
	v_max_f32_e32 v102, 0, v102
	v_max_f32_e32 v103, 0, v103
	v_pk_add_f32 v[88:89], v[88:89], s[100:101] op_sel_hi:[1,0]
	v_pk_add_f32 v[90:91], v[90:91], s[100:101] op_sel_hi:[1,0]
	v_pk_add_f32 v[92:93], v[92:93], s[100:101] op_sel_hi:[1,0]
	v_pk_add_f32 v[94:95], v[94:95], s[100:101] op_sel_hi:[1,0]
	v_cmp_gt_f32_e64 s[16:17], s89, v96
	v_cmp_gt_f32_e64 s[18:19], s89, v97
	v_cmp_gt_f32_e64 s[20:21], s89, v98
	v_cmp_gt_f32_e64 s[22:23], s89, v99
	v_cndmask_b32_e64 v216, 1.0, v2, s[16:17]
	v_cndmask_b32_e64 v208, 1.0, v3, s[16:17]
	v_cndmask_b32_e64 v217, 1.0, v2, s[18:19]
	v_cndmask_b32_e64 v209, 1.0, v3, s[18:19]
	v_cndmask_b32_e64 v218, 1.0, v2, s[20:21]
	v_cndmask_b32_e64 v210, 1.0, v3, s[20:21]
	v_cndmask_b32_e64 v219, 1.0, v2, s[22:23]
	v_cndmask_b32_e64 v211, 1.0, v3, s[22:23]
	v_cmp_gt_f32_e64 s[16:17], s89, v100
	v_cmp_gt_f32_e64 s[18:19], s89, v101
	v_cmp_gt_f32_e64 s[20:21], s89, v102
	v_cmp_gt_f32_e64 s[22:23], s89, v103
	v_cndmask_b32_e64 v220, 1.0, v2, s[16:17]
	v_cndmask_b32_e64 v212, 1.0, v3, s[16:17]
	v_cndmask_b32_e64 v221, 1.0, v2, s[18:19]
	v_cndmask_b32_e64 v213, 1.0, v3, s[18:19]
	v_cndmask_b32_e64 v222, 1.0, v2, s[20:21]
	v_cndmask_b32_e64 v214, 1.0, v3, s[20:21]
	v_cndmask_b32_e64 v223, 1.0, v2, s[22:23]
	v_cndmask_b32_e64 v215, 1.0, v3, s[22:23]
	v_pk_mul_f32 v[96:97], v[96:97], v[216:217]
	v_pk_mul_f32 v[98:99], v[98:99], v[218:219]
	v_pk_mul_f32 v[100:101], v[100:101], v[220:221]
	v_pk_mul_f32 v[102:103], v[102:103], v[222:223]
	v_sqrt_f32_e32 v216, v96
	v_sqrt_f32_e32 v217, v97
	v_sqrt_f32_e32 v218, v98
	v_sqrt_f32_e32 v219, v99
	v_sqrt_f32_e32 v220, v100
	v_sqrt_f32_e32 v221, v101
	v_sqrt_f32_e32 v222, v102
	v_sqrt_f32_e32 v223, v103
	v_rcp_f32_e32 v88, v88
	v_rcp_f32_e32 v89, v89
	v_rcp_f32_e32 v90, v90
	v_rcp_f32_e32 v91, v91
	v_rcp_f32_e32 v92, v92
	v_rcp_f32_e32 v93, v93
	v_rcp_f32_e32 v94, v94
	v_rcp_f32_e32 v95, v95
	v_add_u32_e32 v236, -1, v216
	v_add_u32_e32 v237, -1, v217
	v_add_u32_e32 v238, -1, v218
; #define LAS __attribute__((address_space(3)))
; __device__ __forceinline__ float sigmoidf_(float x) { return __builtin_amdgcn_rcpf(1.f + __expf(-x)); }
; __device__ __forceinline__ void lru_chain(unsigned char* ws_, const float* const* in_, int l_, LAS unsigned char* lds, int tid, int bid, int G) {
;     ...
;                       da = __builtin_amdgcn_mfma_f32_16x16x32_bf16(fa, bfr[c], da, 0, 0, 0); dx = __builtin_amdgcn_mfma_f32_16x16x32_bf16(fx, bfr[c], dx, 0, 0, 0); }
;                   const int ch = 16 * ot + 4 * kq;
;                   const f32x4 ba4 = *(const LAS f32x4*)(PRM + ch), bx4 = *(const LAS f32x4*)(PRM + 64 + ch), sp4 = *(const LAS f32x4*)(PRM + 128 + ch);
;                   const f32x4 u4 = *(const LAS f32x4*)(B_ + tok * 68 + ch); f32x4 a4, b4;
; #pragma unroll
;                   for (int e = 0; e < 4; ++e) { const float rg = sigmoidf_(da[e] + ba4[e]), ig = sigmoidf_(dx[e] + bx4[e]); const float la = -8.0f * rg * sp4[e];
;                       const float av_ = __expf(la); a4[e] = av_; b4[e] = sqrtf(fmaxf(1.0f - av_ * av_, 0.f)) * ig * u4[e]; }
;                   *(LAS f32x4*)(A_ + tok * 68 + ch) = a4; *(LAS f32x4*)(B_ + tok * 68 + ch) = b4; } }
;             __syncthreads();
;             float av[16], bv[16]; float hh = 0.f, aa = 1.f;
; #pragma unroll
;             for (int i = 0; i < 16; ++i) { av[i] = A_[(16 * w + i) * 68 + lane]; bv[i] = B_[(16 * w + i) * 68 + lane]; hh = av[i] * hh + bv[i]; aa *= av[i]; }
;             SA[w * 64 + lane] = aa; SB[w * 64 + lane] = hh;
;             __syncthreads();
;             float hin = CAR[(chunk & 1) * 64 + lane];
;             for (int sgi = 0; sgi < w; ++sgi) hin = SA[sgi * 64 + lane] * hin + SB[sgi * 64 + lane];
	v_add_u32_e32 v239, -1, v219
	v_add_u32_e32 v240, -1, v220
	v_add_u32_e32 v241, -1, v221
	v_add_u32_e32 v242, -1, v222
	v_add_u32_e32 v243, -1, v223
	v_pk_fma_f32 v[244:245], v[236:237], v[216:217], v[96:97] neg_lo:[1,0,0] neg_hi:[1,0,0]
	v_pk_fma_f32 v[246:247], v[238:239], v[218:219], v[98:99] neg_lo:[1,0,0] neg_hi:[1,0,0]
	v_pk_fma_f32 v[248:249], v[240:241], v[220:221], v[100:101] neg_lo:[1,0,0] neg_hi:[1,0,0]
	v_pk_fma_f32 v[250:251], v[242:243], v[222:223], v[102:103] neg_lo:[1,0,0] neg_hi:[1,0,0]
	v_add_u32_e32 v180, 1, v216
	v_add_u32_e32 v181, 1, v217
	v_add_u32_e32 v182, 1, v218
	v_add_u32_e32 v183, 1, v219
	v_add_u32_e32 v232, 1, v220
	v_add_u32_e32 v233, 1, v221
	v_add_u32_e32 v234, 1, v222
	v_add_u32_e32 v235, 1, v223
	v_cmp_ge_f32_e64 s[16:17], 0, v244
	v_cmp_ge_f32_e64 s[18:19], 0, v245
	v_cmp_ge_f32_e64 s[20:21], 0, v246
	v_cmp_ge_f32_e64 s[22:23], 0, v247
	v_cndmask_b32_e64 v236, v216, v236, s[16:17]
	v_cndmask_b32_e64 v237, v217, v237, s[18:19]
	v_cndmask_b32_e64 v238, v218, v238, s[20:21]
	v_cndmask_b32_e64 v239, v219, v239, s[22:23]
	v_cmp_ge_f32_e64 s[16:17], 0, v248
	v_cmp_ge_f32_e64 s[18:19], 0, v249
	v_cmp_ge_f32_e64 s[20:21], 0, v250
	v_cmp_ge_f32_e64 s[22:23], 0, v251
	v_cndmask_b32_e64 v240, v220, v240, s[16:17]
	v_cndmask_b32_e64 v241, v221, v241, s[18:19]
	v_cndmask_b32_e64 v242, v222, v242, s[20:21]
	v_cndmask_b32_e64 v243, v223, v243, s[22:23]
	v_pk_fma_f32 v[244:245], v[180:181], v[216:217], v[96:97] neg_lo:[1,0,0] neg_hi:[1,0,0]
	v_pk_fma_f32 v[246:247], v[182:183], v[218:219], v[98:99] neg_lo:[1,0,0] neg_hi:[1,0,0]
	v_pk_fma_f32 v[248:249], v[232:233], v[220:221], v[100:101] neg_lo:[1,0,0] neg_hi:[1,0,0]
	v_pk_fma_f32 v[250:251], v[234:235], v[222:223], v[102:103] neg_lo:[1,0,0] neg_hi:[1,0,0]
	v_cmp_lt_f32_e64 s[16:17], 0, v244
	v_cmp_lt_f32_e64 s[18:19], 0, v245
	v_cmp_lt_f32_e64 s[20:21], 0, v246
	v_cmp_lt_f32_e64 s[22:23], 0, v247
	v_cndmask_b32_e64 v236, v236, v180, s[16:17]
	v_cndmask_b32_e64 v237, v237, v181, s[18:19]
	v_cndmask_b32_e64 v238, v238, v182, s[20:21]
	v_cndmask_b32_e64 v239, v239, v183, s[22:23]
	v_cmp_lt_f32_e64 s[16:17], 0, v248
	v_cmp_lt_f32_e64 s[18:19], 0, v249
	v_cmp_lt_f32_e64 s[20:21], 0, v250
	v_cmp_lt_f32_e64 s[22:23], 0, v251
	v_cndmask_b32_e64 v240, v240, v232, s[16:17]
	v_cndmask_b32_e64 v241, v241, v233, s[18:19]
	v_cndmask_b32_e64 v242, v242, v234, s[20:21]
	v_cndmask_b32_e64 v243, v243, v235, s[22:23]
	v_pk_mul_f32 v[236:237], v[236:237], v[208:209]
	v_pk_mul_f32 v[238:239], v[238:239], v[210:211]
	v_pk_mul_f32 v[240:241], v[240:241], v[212:213]
	v_pk_mul_f32 v[242:243], v[242:243], v[214:215]
	v_cmp_class_f32_e64 s[16:17], v96, v175
	v_cmp_class_f32_e64 s[18:19], v97, v175
	v_cmp_class_f32_e64 s[20:21], v98, v175
	v_cmp_class_f32_e64 s[22:23], v99, v175
	v_cndmask_b32_e64 v236, v236, v96, s[16:17]
	v_cndmask_b32_e64 v237, v237, v97, s[18:19]
	v_cndmask_b32_e64 v238, v238, v98, s[20:21]
	v_cndmask_b32_e64 v239, v239, v99, s[22:23]
	v_cmp_class_f32_e64 s[16:17], v100, v175
	v_cmp_class_f32_e64 s[18:19], v101, v175
	v_cmp_class_f32_e64 s[20:21], v102, v175
	v_cmp_class_f32_e64 s[22:23], v103, v175
	v_cndmask_b32_e64 v240, v240, v100, s[16:17]
	v_cndmask_b32_e64 v241, v241, v101, s[18:19]
	v_cndmask_b32_e64 v242, v242, v102, s[20:21]
	v_cndmask_b32_e64 v243, v243, v103, s[22:23]
	v_pk_mul_f32 v[88:89], v[88:89], v[236:237]
	v_pk_mul_f32 v[90:91], v[90:91], v[238:239]
	v_pk_mul_f32 v[92:93], v[92:93], v[240:241]
	v_pk_mul_f32 v[94:95], v[94:95], v[242:243]
	v_pk_mul_f32 v[88:89], v[224:225], v[88:89]
	v_pk_mul_f32 v[90:91], v[226:227], v[90:91]
	v_pk_mul_f32 v[92:93], v[228:229], v[92:93]
	v_pk_mul_f32 v[94:95], v[230:231], v[94:95]
	ds_write_b128 v169, v[80:83] offset:18560
	ds_write_b128 v169, v[88:91] offset:53376
	ds_write_b128 v169, v[84:87] offset:18624
	ds_write_b128 v169, v[92:95] offset:53440
	v_add_u32_e32 v1, 0x4800, v197
	v_add_u32_e32 v2, 0xd000, v197
	v_add_u32_e32 v102, 0xdc00, v197
	s_waitcnt lgkmcnt(0)
	s_barrier
	ds_read2_b32 v[100:101], v1 offset1:68
	ds_read2_b32 v[96:97], v2 offset1:68
	ds_read2_b32 v[98:99], v1 offset0:136 offset1:204
	ds_read2_b32 v[92:93], v2 offset0:136 offset1:204
	s_andn2_b64 vcc, exec, s[48:49]
	s_waitcnt lgkmcnt(3)
	v_mul_f32_e32 v72, v100, v101
	s_waitcnt lgkmcnt(2)
	v_fma_f32 v3, 0, v100, v96
	v_fma_f32 v3, v3, v101, v97
	s_waitcnt lgkmcnt(0)
	v_fma_f32 v1, v3, v98, v92
	v_add_u32_e32 v3, 0x4c00, v197
	ds_read2_b32 v[94:95], v3 offset0:16 offset1:84
	v_mul_f32_e32 v2, v72, v98
	v_add_u32_e32 v72, 0xd400, v197
	ds_read2_b32 v[88:89], v72 offset0:16 offset1:84
	ds_read2_b32 v[90:91], v3 offset0:152 offset1:220
	ds_read2_b32 v[84:85], v72 offset0:152 offset1:220
	v_add_u32_e32 v3, 0x5000, v197
	v_mul_f32_e32 v2, v2, v99
	ds_read2_b32 v[86:87], v3 offset0:32 offset1:100
	s_waitcnt lgkmcnt(4)
	v_mul_f32_e32 v2, v2, v94
	v_mul_f32_e32 v2, v2, v95
	v_add_u32_e32 v72, 0xd800, v197
	s_waitcnt lgkmcnt(2)
	v_mul_f32_e32 v2, v2, v90
	ds_read2_b32 v[80:81], v72 offset0:32 offset1:100
	ds_read2_b32 v[82:83], v3 offset0:168 offset1:236
	ds_read2_b32 v[76:77], v72 offset0:168 offset1:236
	v_add_u32_e32 v3, 0x5400, v197
	v_fma_f32 v1, v1, v99, v93
	v_mul_f32_e32 v2, v2, v91
	ds_read2_b32 v[78:79], v3 offset0:48 offset1:116
	v_fma_f32 v1, v1, v94, v88
	s_waitcnt lgkmcnt(4)
	v_mul_f32_e32 v2, v2, v86
	v_fma_f32 v1, v1, v95, v89
	v_mul_f32_e32 v2, v2, v87
	v_fma_f32 v1, v1, v90, v84
	s_waitcnt lgkmcnt(2)
	v_mul_f32_e32 v2, v2, v82
	v_fma_f32 v1, v1, v91, v85
	v_mul_f32_e32 v2, v2, v83
	ds_read2_b32 v[72:73], v102 offset0:48 offset1:116
	v_fma_f32 v1, v1, v86, v80
	s_waitcnt lgkmcnt(1)
	v_mul_f32_e32 v2, v2, v78
	v_fma_f32 v1, v1, v87, v81
	v_mul_f32_e32 v103, v2, v79
	ds_read2_b32 v[74:75], v3 offset0:184 offset1:252
	ds_read2_b32 v[2:3], v102 offset0:184 offset1:252
	v_fma_f32 v1, v1, v82, v76
	v_fma_f32 v1, v1, v83, v77
	s_waitcnt lgkmcnt(2)
	v_fma_f32 v1, v1, v78, v72
	v_fma_f32 v1, v1, v79, v73
	s_waitcnt lgkmcnt(0)
	v_fma_f32 v1, v1, v74, v2
	v_mul_f32_e32 v102, v103, v74
	v_fma_f32 v1, v1, v75, v3
	v_mul_f32_e32 v102, v102, v75
	ds_write_b32 v162, v102
	ds_write_b32 v163, v1
	v_lshl_add_u32 v1, s2, 2, v159
	s_waitcnt lgkmcnt(0)
	s_barrier
	ds_read_b32 v1, v1
	v_mov_b32_e32 v102, v198
	s_cbranch_vccnz .LBB0_203
